# GEMM phases: workgroup index rebuilt from hardware XCC id and per-XCD arrival rank (true XCD affinity for the tile order)
# baseline (speedup 1.0000x reference)
.LBB0_7:
	v_readlane_b32 s0, v252, 7
	s_cmp_le_i32 s0, s56
	s_cbranch_scc1 .LBB0_1418
	v_readlane_b32 s0, v252, 7
	s_cmp_lt_i32 s0, 0x186a1
	s_cselect_b64 s[0:1], -1, 0
	v_writelane_b32 v252, s0, 8
	v_and_b32_e32 v202, 0x3ff, v0
	v_and_b32_e32 v0, 0x3fffffff, v0
	v_writelane_b32 v252, s1, 9
	s_add_u32 s0, s12, 0x12cd8200
	s_addc_u32 s1, s13, 0
	v_writelane_b32 v252, s0, 10
	v_cmp_eq_u32_e64 s[92:93], 0, v202
	v_mbcnt_lo_u32_b32 v2, -1, 0
	v_writelane_b32 v252, s1, 11
	s_add_u32 s0, s12, 0x12cd8400
	s_addc_u32 s1, s13, 0
	v_writelane_b32 v252, s0, 12
	v_mov_b32_e32 v1, 0
	v_mov_b64_e32 v[170:171], 0x200
	v_writelane_b32 v252, s1, 13
	s_getreg_b32 s96, hwreg(HW_REG_XCC_ID, 0, 4)
	s_and_b32 s96, s96, 7
	s_lshl_b32 s97, s96, 6
	s_add_u32 s98, s12, 0x12cdb800
	s_addc_u32 s99, s13, 0
	s_add_u32 s98, s98, s97
	s_addc_u32 s99, s99, 0
	s_and_saveexec_b64 s[0:1], s[92:93]
	s_cbranch_execz .Lrk_skip
	v_mov_b32_e32 v5, 1
	s_nop 0
	global_atomic_add v5, v1, v5, s[98:99] sc0
	s_waitcnt vmcnt(0)
	v_lshlrev_b32_e32 v5, 3, v5
	v_add_u32_e32 v5, s96, v5
	v_and_b32_e32 v5, 0xff, v5
	v_mov_b32_e32 v6, 0x21fe4
	ds_write_b32 v6, v5
.Lrk_skip:
	s_or_b64 exec, exec, s[0:1]
	s_waitcnt lgkmcnt(0)
	s_barrier
	v_mov_b32_e32 v6, 0x21fe4
	ds_read_b32 v6, v6
	s_waitcnt lgkmcnt(0)
	v_readfirstlane_b32 s96, v6
	s_nop 3
	v_writelane_b32 v255, s96, 2
	s_add_u32 s0, s12, 0x12cd8500
	s_addc_u32 s1, s13, 0
	v_writelane_b32 v252, s0, 14
	v_mov_b64_e32 v[172:173], 0x1ff
	v_mov_b32_e32 v203, 0x358637bd
	v_writelane_b32 v252, s1, 15
	s_add_u32 s0, s12, 0x12cd8600
	s_addc_u32 s1, s13, 0
	v_writelane_b32 v252, s0, 16
	v_mov_b32_e32 v204, 0x3ecc95a3
	v_mov_b32_e32 v205, 0x38d1b717
	v_writelane_b32 v252, s1, 17
	s_add_u32 s0, s12, 0x12cd8700
	s_addc_u32 s1, s13, 0
	v_writelane_b32 v252, s0, 18
	v_mov_b32_e32 v206, 0xc0447cbd
	v_mov_b32_e32 v207, 1
	v_writelane_b32 v252, s1, 19
	s_add_u32 s0, s12, 0x12cd8800
	s_addc_u32 s1, s13, 0
	v_writelane_b32 v252, s0, 20
	v_not_b32_e32 v208, 63
	v_mov_b32_e32 v209, 0x42800000
	v_writelane_b32 v252, s1, 21
	s_add_u32 s0, s12, 0x12cd8900
	s_addc_u32 s1, s13, 0
	v_writelane_b32 v252, s0, 22
	v_mbcnt_hi_u32_b32 v210, -1, v2
	v_mov_b32_e32 v211, 0x7f800000
	v_writelane_b32 v252, s1, 23
	s_add_u32 s0, s12, 0x12cd8a00
	s_addc_u32 s1, s13, 0
	v_writelane_b32 v252, s0, 24
	v_mov_b32_e32 v212, 0x7fc00000
	v_mov_b32_e32 v213, 0xff800000
	v_writelane_b32 v252, s1, 25
	s_add_u32 s0, s12, 0x12cd8b00
	s_addc_u32 s1, s13, 0
	v_writelane_b32 v252, s0, 26
	v_mov_b32_e32 v174, 0x3f317218
	v_mov_b32_e32 v214, 2
	v_writelane_b32 v252, s1, 27
	s_add_u32 s0, s12, 0x12cd8c00
	s_addc_u32 s1, s13, 0
	v_writelane_b32 v252, s0, 28
	v_mov_b32_e32 v215, 0xff60
	v_mov_b32_e32 v216, 0xff5c
	v_writelane_b32 v252, s1, 29
	s_add_u32 s0, s12, 0x12cd8d00
	s_addc_u32 s1, s13, 0
	v_writelane_b32 v252, s0, 30
	v_mov_b32_e32 v217, 0xff1c
	v_mov_b32_e32 v218, 0xfdbc
	v_writelane_b32 v252, s1, 31
	s_add_u32 s0, s12, 0x12cd8e00
	s_addc_u32 s1, s13, 0
	v_writelane_b32 v252, s0, 32
	v_mov_b32_e32 v219, 30
	v_mov_b32_e32 v220, 6
	v_writelane_b32 v252, s1, 33
	s_add_u32 s0, s12, 0x12cd8f00
	s_addc_u32 s1, s13, 0
	v_writelane_b32 v252, s0, 34
	v_mov_b32_e32 v221, 5
	v_mov_b32_e32 v222, 24
	v_writelane_b32 v252, s1, 35
	s_add_u32 s0, s12, 0x12cd9000
	s_addc_u32 s1, s13, 0
	v_writelane_b32 v252, s0, 36
	v_mov_b32_e32 v223, 8
	v_mov_b32_e32 v224, 0x100
	v_writelane_b32 v252, s1, 37
	s_add_u32 s0, s12, 0x12cd9100
	s_addc_u32 s1, s13, 0
	v_writelane_b32 v252, s0, 38
	v_mov_b32_e32 v225, 0x400
	v_mov_b32_e32 v226, 0x80000
	v_writelane_b32 v252, s1, 39
	s_add_u32 s0, s12, 0x12cd9200
	s_addc_u32 s1, s13, 0
	v_writelane_b32 v252, s0, 40
	s_mov_b32 s57, 0xe0000
	s_movk_i32 s85, 0x2000
	v_writelane_b32 v252, s1, 41
	s_add_u32 s0, s12, 0x12cd9300
	s_addc_u32 s1, s13, 0
	v_writelane_b32 v252, s0, 42
	s_cmp_eq_u32 s8, 15
	s_movk_i32 s29, 0x210
	v_writelane_b32 v252, s1, 43
	s_cselect_b64 s[0:1], -1, 0
	v_writelane_b32 v252, s0, 44
	s_cmp_eq_u32 s8, 14
	s_mov_b32 s90, 0xbfb8aa3b
	v_writelane_b32 v252, s1, 45
	s_cselect_b64 s[0:1], -1, 0
	v_writelane_b32 v252, s0, 46
	s_cmp_eq_u32 s8, 13
	s_movk_i32 s84, 0x104
	v_writelane_b32 v252, s1, 47
	s_cselect_b64 s[0:1], -1, 0
	v_writelane_b32 v252, s0, 48
	s_cmp_eq_u32 s8, 12
	s_movk_i32 s37, 0x1000
	v_writelane_b32 v252, s1, 49
	s_cselect_b64 s[0:1], -1, 0
	v_writelane_b32 v252, s0, 50
	s_cmp_eq_u32 s8, 11
	s_movk_i32 s27, 0x7fff
	v_writelane_b32 v252, s1, 51
	s_cselect_b64 s[0:1], -1, 0
	v_writelane_b32 v252, s0, 52
	s_cmp_eq_u32 s8, 10
	s_movk_i32 s68, 0x3000
	v_writelane_b32 v252, s1, 53
	s_cselect_b64 s[0:1], -1, 0
	v_writelane_b32 v252, s0, 54
	s_cmp_eq_u32 s8, 9
	s_mov_b32 s86, 0x5040100
	v_writelane_b32 v252, s1, 55
	s_cselect_b64 s[0:1], -1, 0
	v_writelane_b32 v252, s0, 56
	s_cmp_eq_u32 s8, 8
	s_mov_b32 s87, 0x800000
	v_writelane_b32 v252, s1, 57
	s_cselect_b64 s[0:1], -1, 0
	v_writelane_b32 v252, s0, 58
	s_cmp_eq_u32 s8, 7
	s_movk_i32 s91, 0xfff
	v_writelane_b32 v252, s1, 59
	s_cselect_b64 s[0:1], -1, 0
	v_writelane_b32 v252, s0, 60
	s_cmp_eq_u32 s8, 6
	s_movk_i32 s88, 0x1400
	v_writelane_b32 v252, s1, 61
	s_cselect_b64 s[0:1], -1, 0
	v_writelane_b32 v252, s0, 62
	s_cmp_eq_u32 s8, 5
	s_movk_i32 s89, 0x1ff
	v_writelane_b32 v252, s1, 63
	s_cselect_b64 s[0:1], -1, 0
	v_writelane_b32 v253, s0, 0
	s_cmp_eq_u32 s8, 4
	s_mov_b32 s36, 0x3f2aaaab
	v_writelane_b32 v253, s1, 1
	s_cselect_b64 s[0:1], -1, 0
	v_writelane_b32 v253, s0, 2
	s_cmp_eq_u32 s8, 3
	s_mov_b32 s78, 0x3f317218
	v_writelane_b32 v253, s1, 3
	s_cselect_b64 s[0:1], -1, 0
	v_writelane_b32 v253, s0, 4
	s_cmp_eq_u32 s8, 2
	s_mov_b32 s79, 0x7f800000
	v_writelane_b32 v253, s1, 5
	s_cselect_b64 s[0:1], -1, 0
	v_writelane_b32 v253, s0, 6
	s_cmp_eq_u32 s8, 1
	s_mov_b32 s33, 0x2aaaaaab
	v_writelane_b32 v253, s1, 7
	s_cselect_b64 s[0:1], -1, 0
	v_writelane_b32 v253, s0, 8
	s_cmp_eq_u32 s8, 0
	s_mov_b32 s31, 0
	v_writelane_b32 v253, s1, 9
	s_cselect_b64 s[0:1], -1, 0
	s_lshl_b32 s4, s8, 8
	s_add_u32 s2, s2, s4
	v_writelane_b32 v253, s0, 10
	s_addc_u32 s3, s3, 0
	s_mov_b64 s[34:35], 0x80
	v_writelane_b32 v253, s1, 11
	s_add_u32 s0, s2, 0x1400
	s_addc_u32 s1, s3, 0
	v_writelane_b32 v253, s0, 12
	v_readlane_b32 s2, v252, 3
	v_readlane_b32 s3, v252, 4
	v_writelane_b32 v253, s1, 13
	s_add_u32 s0, s12, 0x12cdb400
	s_addc_u32 s1, s13, 0
	v_writelane_b32 v253, s0, 14
	s_add_i32 s69, 0, 0x21fe0
	s_mov_b32 s26, 0x3dd53b94
	v_writelane_b32 v253, s1, 15
	v_readlane_b32 s0, v252, 1
	v_readlane_b32 s1, v252, 2
	s_mul_i32 s0, s1, s0
	s_load_dword s1, s[2:3], 0x158
	s_mov_b32 s2, 0x33800000
	s_mov_b64 s[94:95], 0x400
	s_mov_b64 s[60:61], 0x1000
	s_mov_b32 s28, 0x3e0293ee
	s_waitcnt lgkmcnt(0)
	s_mul_i32 s0, s0, s1
	v_writelane_b32 v253, s0, 16
	s_add_i32 s0, 0, 0x20000
	v_writelane_b32 v253, s0, 17
	s_add_i32 s0, 0, 0x7fbe
	v_writelane_b32 v253, s0, 18
	s_add_i32 s0, 0, 0x13800
	v_writelane_b32 v253, s0, 19
	s_add_i32 s0, 0, 0x19000
	v_writelane_b32 v253, s0, 20
	s_add_i32 s0, 0, 0x17000
	v_writelane_b32 v253, s0, 21
	s_add_i32 s0, 0, 0xd00
	v_writelane_b32 v253, s0, 22
	s_add_i32 s0, 0, 0x21ff0
	v_writelane_b32 v253, s0, 23
	s_add_i32 s0, 0, 0x21ff4
	v_writelane_b32 v253, s0, 24
	v_cmp_eq_u32_e64 s[0:1], 0, v0
	s_nop 1
	v_writelane_b32 v253, s0, 25
	s_nop 1
	v_writelane_b32 v253, s1, 26
	v_writelane_b32 v253, s69, 27
	v_writelane_b32 v253, s92, 28
	s_nop 1
	v_writelane_b32 v253, s93, 29
	s_branch .LBB0_13

.LBB0_13:
	v_readlane_b32 s0, v252, 0
	v_readlane_b32 s8, v252, 3
	s_mov_b32 s96, 0xab4b55a4
	s_mov_b32 s97, 6
	s_bitcmp1_b64 s[96:97], s56
	s_cbranch_scc0 .Lid_keep
	v_readlane_b32 s0, v255, 2
	s_nop 3
.Lid_keep:
	s_mov_b32 s70, s0
	v_readlane_b32 s0, v252, 1
	v_readlane_b32 s9, v252, 4
	s_mov_b32 s72, s0
	s_load_dwordx2 s[80:81], s[8:9], 0x140
	v_readlane_b32 s1, v252, 2
	s_mov_b64 s[10:11], -1
	s_mov_b64 s[12:13], 0
	s_cmp_lt_i32 s56, 35
	s_mov_b64 s[0:1], 0
	s_waitcnt lgkmcnt(0)
	s_mov_b64 s[100:101], s[80:81]
	s_mov_b64 s[4:5], -1
	s_cbranch_scc1 .LBB0_17
	s_cmp_eq_u32 s56, 35
	s_mov_b64 s[0:1], -1
	s_cbranch_scc0 .LBB0_16
	s_mov_b64 s[0:1], 0
